# NSA selected/window tiles: softmax reference folded into the MFMA accumulator init (16 fewer VALU per 32-key sub-tile)
# speedup vs baseline: 1.0017x; 1.0017x over previous
; #define LAS __attribute__((address_space(3)))
; #define ST_V(base, v) do { LAS unsigned char* vp_ = (base) + voff; *(LAS u32x2*)vp_ = (u32x2){(v).x, (v).y}; *(LAS u32x2*)(vp_ + 8) = (u32x2){(v).z, (v).w}; } while (0)
; DI void nsa_unit(const Params& p, LAS unsigned char* lds, unsigned char* ldsg, int bg, int qt, int tid) {
;     ...
;     const int kq = tid >> 3, kch = tid & 7;
;     const int toff = kq * 144 + kch * 16, voff = 9216 + kq * 136 + kch * 16;
;     ...
;     {
;         const int nl = NL[0];
;         const bf16_t* Ksrc = PROJ + (tokb + kq) * NPROJ + 2112 + g * 64 + 8 * kch;
;         const bf16_t* Vsrc = VST + ((size_t)(bg * 64 + kq)) * S_ + 8 * kch;
;         f32x16 o[2];
; #pragma unroll
;         for (int db = 0; db < 2; ++db)
; #pragma unroll
;             for (int i = 0; i < 16; ++i) o[db][i] = 0.f;
;         float m = -1e20f, l = 0.f;
;         u32x4 rk1, rv1, rk2, rv2;
;         { const int nb = LIST[0]; rk1 = *(const u32x4*)(Ksrc + (size_t)(64 * nb) * NPROJ); rv1 = *(const u32x4*)(Vsrc + 64 * nb); }
;         *(LAS u32x4*)(lds + toff) = rk1; ST_V(lds, rv1);
;         if (nl > 1) { const int nb = LIST[1]; rk1 = *(const u32x4*)(Ksrc + (size_t)(64 * nb) * NPROJ); rv1 = *(const u32x4*)(Vsrc + 64 * nb); }
;         __syncthreads();
;         int cb = 0;
;         for (int i = 0; i < nl; ++i) {
;             const int nb = LIST[i];
;             if (i + 2 < nl) { const int nb2 = LIST[i + 2]; rk2 = *(const u32x4*)(Ksrc + (size_t)(64 * nb2) * NPROJ); rv2 = *(const u32x4*)(Vsrc + 64 * nb2); }
;             const bool lanesel = (SEL[(4 * w + qi) * 4 + (nb >> 5)] >> (nb & 31)) & 1u;
.LBB0_818:
	s_movk_i32 s2, 0x88
	s_cmp_lt_i32 s8, 1
	v_mul_u32_u24_e32 v15, 0x88, v68
	v_mad_u32_u24 v176, v68, s2, v168
	s_waitcnt lgkmcnt(0)
	s_barrier
	s_cbranch_scc1 .LBB0_839
	v_or_b32_e32 v10, s49, v67
	s_add_i32 s2, 0, 0x26400
	v_lshl_add_u32 v113, v10, 4, s2
	v_lshlrev_b32_e32 v10, 2, v114
	v_mov_b32_e32 v175, 0
	v_sub_u32_e32 v117, v150, v10
	v_mov_b32_e32 v153, v152
	v_mov_b32_e32 v118, 0xe0ad78ec
	v_mov_b32_e32 v248, 0
	s_mov_b32 s9, 0
	v_readlane_b32 s10, v234, 35
	s_mov_b32 s11, 0
	v_mov_b32_e32 v48, 0
	v_mov_b32_e32 v49, v175
	v_mov_b32_e32 v50, v175
	v_mov_b32_e32 v51, v175
	v_mov_b32_e32 v52, v175
	v_mov_b32_e32 v53, v175
	v_mov_b32_e32 v54, v175
	v_mov_b32_e32 v55, v175
	v_mov_b32_e32 v56, v175
	v_mov_b32_e32 v57, v175
	v_mov_b32_e32 v58, v175
	v_mov_b32_e32 v59, v175
	v_mov_b32_e32 v60, v175
	v_mov_b32_e32 v61, v175
	v_mov_b32_e32 v62, v175
	v_mov_b32_e32 v63, v175
	v_mov_b32_e32 v64, v175
	v_mov_b32_e32 v65, v175
	v_mov_b32_e32 v66, v175
	v_mov_b32_e32 v67, v175
	v_mov_b32_e32 v68, v175
	v_mov_b32_e32 v69, v175
	v_mov_b32_e32 v70, v175
	v_mov_b32_e32 v71, v175
	v_mov_b32_e32 v72, v175
	v_mov_b32_e32 v73, v175
	v_mov_b32_e32 v74, v175
	v_mov_b32_e32 v75, v175
	v_mov_b32_e32 v76, v175
	v_mov_b32_e32 v77, v175
	v_mov_b32_e32 v78, v175
	v_mov_b32_e32 v79, v175

; #define LAS __attribute__((address_space(3)))
; DI float xhalf_max(float v) { unsigned a = __builtin_bit_cast(unsigned, v), b = a; swap32(a, b); return fmaxf(__builtin_bit_cast(float, a), __builtin_bit_cast(float, b)); }
; DI float fexp2(float x) { return __builtin_amdgcn_exp2f(x); }
; #define MFMA32(a, b, c) __builtin_amdgcn_mfma_f32_32x32x16_bf16((a), (b), (c), 0, 0, 0)
; template <int MODE>
; DI void nsa_tile(LAS const unsigned char* buf, const bf16x8 (&qf)[4], f32x16 (&o)[2], float& m, float& l, int kbase0, int t, bool lanesel, float slope2, int c, int hi) {
;     ...
;     for (int sub = 0; sub < 2; ++sub) {
;         const int klo = kbase0 + 32 * sub;
;         bool full, none;
;         if (MODE == 0) { full = lanesel && (klo + 31 <= t); none = !lanesel || (klo > t); }
;         else { full = (klo + 31 <= t) && (klo >= t - 511); none = (klo > t) || (klo + 31 < t - 511); }
;         if (__all(none)) continue;
;         int dbase = t - klo - 4 * hi;
;         asm volatile("" : "+v"(dbase));
;         const float b0 = none ? -1e30f : -slope2 * (float)dbase;
;         f32x16 s;
; #pragma unroll
;         for (int i = 0; i < 16; ++i) s[i] = fmaf(slope2, (float)((i & 3) + 8 * (i >> 2)), b0);
; #pragma unroll
;         for (int st = 0; st < 4; ++st) {
;             const bf16x8 a = *(LAS const bf16x8*)(buf + (32 * sub + c) * 144 + st * 32 + hi * 16);
;             s = MFMA32(a, qf[st], s);
;         }
;         if (__any(!full && !none)) {
; #pragma unroll
;             for (int i = 0; i < 16; ++i) {
;                 const int dist = dbase - ((i & 3) + 8 * (i >> 2));
;                 const bool valid = (MODE == 0) ? (lanesel && dist >= 0) : ((unsigned)dist < 512u);
;                 if (!valid) s[i] = -1e30f;
;             }
;         }
;         float mx = max16(s);
;         mx = xhalf_max(mx);
;         if (__any(mx > m + 8.f)) {
;             const float mn = fmaxf(m, mx), alpha = fexp2(m - mn); m = mn; l *= alpha;
;             o[0] = o[0] * alpha; o[1] = o[1] * alpha;
;         }
.LBB0_822:
	s_ashr_i32 s2, s4, 5
	v_lshl_add_u32 v80, s2, 2, v113
	ds_read_b32 v80, v80
	s_and_b32 s2, s4, 31
	s_waitcnt lgkmcnt(0)
	v_lshrrev_b32_e32 v81, s4, v80
	v_bfe_u32 v80, v80, s2, 1
	v_and_b32_e32 v81, 1, v81
	v_cmp_ne_u32_e32 vcc, 0, v80
	v_cmp_eq_u32_e64 s[2:3], 1, v81
	s_cbranch_vccz .LBB0_835
	s_lshl_b32 s15, s4, 6
	s_xor_b64 s[6:7], s[2:3], -1
	v_cmp_gt_i32_e32 vcc, s15, v150
	s_mul_i32 s5, s11, 0x4600
	s_or_b64 vcc, vcc, s[6:7]
	s_add_i32 s14, s5, 0
	v_cndmask_b32_e64 v81, 0, 1, vcc
	v_add_u32_e32 v80, s14, v0
	v_cmp_ne_u32_e64 s[4:5], 0, v81
	s_cmp_eq_u64 s[4:5], exec
	v_add_u32_e32 v119, v80, v171
	s_cbranch_scc1 .LBB0_829
	v_subrev_u32_e32 v120, s15, v117
	ds_read_b128 v[122:125], v119
	v_cvt_f32_i32_e32 v80, v120
	s_or_b32 s4, s15, 31
	v_cmp_gt_i32_e64 s[4:5], s4, v150
	s_or_b64 s[4:5], s[6:7], s[4:5]
	v_mul_f32_e64 v80, -v152, v80
	v_cndmask_b32_e32 v94, v80, v164, vcc
	v_sub_f32_e32 v94, v94, v248
	v_fma_f32 v80, 0, v152, v94
	v_add_f32_e32 v81, v152, v94
	v_pk_fma_f32 v[82:83], v[152:153], s[72:73], v[94:95] op_sel_hi:[1,1,0]
	v_pk_fma_f32 v[84:85], v[152:153], s[74:75], v[94:95] op_sel_hi:[1,1,0]
	v_pk_fma_f32 v[86:87], v[152:153], s[76:77], v[94:95] op_sel_hi:[1,1,0]
	v_pk_fma_f32 v[88:89], v[152:153], s[70:71], v[94:95] op_sel_hi:[1,1,0]
	v_pk_fma_f32 v[90:91], v[152:153], s[78:79], v[94:95] op_sel_hi:[1,1,0]
	v_pk_fma_f32 v[92:93], v[152:153], s[80:81], v[94:95] op_sel_hi:[1,1,0]
	v_pk_fma_f32 v[94:95], v[152:153], s[82:83], v[94:95] op_sel_hi:[1,1,0]
	s_xor_b64 s[4:5], vcc, s[4:5]
	v_cndmask_b32_e64 v121, 0, 1, s[4:5]
	s_waitcnt lgkmcnt(0)
	v_mfma_f32_32x32x16_bf16 v[80:95], v[122:125], v[128:131], v[80:95]
	ds_read_b128 v[122:125], v119 offset:32
	v_cmp_ne_u32_e32 vcc, 0, v121
	s_waitcnt lgkmcnt(0)
	v_mfma_f32_32x32x16_bf16 v[80:95], v[122:125], v[132:135], v[80:95]
	ds_read_b128 v[122:125], v119 offset:64
	s_waitcnt lgkmcnt(0)
	v_mfma_f32_32x32x16_bf16 v[80:95], v[122:125], v[136:139], v[80:95]
	ds_read_b128 v[122:125], v119 offset:96
	s_waitcnt lgkmcnt(0)
	v_mfma_f32_32x32x16_bf16 v[80:95], v[122:125], v[140:143], v[80:95]
	s_cbranch_vccz .LBB0_826
	v_cmp_lt_i32_e32 vcc, -1, v120
	s_and_b64 vcc, s[2:3], vcc
	s_nop 8
	v_cndmask_b32_e32 v80, v164, v80, vcc
	v_cmp_lt_i32_e32 vcc, 0, v120
	s_and_b64 vcc, s[2:3], vcc
	s_nop 0
	v_cndmask_b32_e32 v81, v164, v81, vcc
	v_cmp_lt_i32_e32 vcc, 1, v120
	s_and_b64 vcc, s[2:3], vcc
	s_nop 0
	v_cndmask_b32_e32 v82, v164, v82, vcc
	v_cmp_lt_i32_e32 vcc, 2, v120
	s_and_b64 vcc, s[2:3], vcc
	s_nop 0
	v_cndmask_b32_e32 v83, v164, v83, vcc
	v_cmp_lt_i32_e32 vcc, 7, v120
	s_and_b64 vcc, s[2:3], vcc
	s_nop 0
	v_cndmask_b32_e32 v84, v164, v84, vcc
	v_cmp_lt_i32_e32 vcc, 8, v120
	s_and_b64 vcc, s[2:3], vcc
	s_nop 0
	v_cndmask_b32_e32 v85, v164, v85, vcc
	v_cmp_lt_i32_e32 vcc, 9, v120
	s_and_b64 vcc, s[2:3], vcc
	s_nop 0
	v_cndmask_b32_e32 v86, v164, v86, vcc
	v_cmp_lt_i32_e32 vcc, 10, v120
	s_and_b64 vcc, s[2:3], vcc
	s_nop 0
	v_cndmask_b32_e32 v87, v164, v87, vcc
	v_cmp_lt_i32_e32 vcc, 15, v120
	s_and_b64 vcc, s[2:3], vcc
	s_nop 0
	v_cndmask_b32_e32 v88, v164, v88, vcc
	v_cmp_lt_i32_e32 vcc, 16, v120
	s_and_b64 vcc, s[2:3], vcc
	s_nop 0
	v_cndmask_b32_e32 v89, v164, v89, vcc
	v_cmp_lt_i32_e32 vcc, 17, v120
	s_and_b64 vcc, s[2:3], vcc
	s_nop 0
	v_cndmask_b32_e32 v90, v164, v90, vcc
	v_cmp_lt_i32_e32 vcc, 18, v120
	s_and_b64 vcc, s[2:3], vcc
	s_nop 0
	v_cndmask_b32_e32 v91, v164, v91, vcc
	v_cmp_lt_i32_e32 vcc, 23, v120
	s_and_b64 vcc, s[2:3], vcc
	s_nop 0
	v_cndmask_b32_e32 v92, v164, v92, vcc
	v_cmp_lt_i32_e32 vcc, 24, v120
	s_and_b64 vcc, s[2:3], vcc
	s_nop 0
	v_cndmask_b32_e32 v93, v164, v93, vcc
	v_cmp_lt_i32_e32 vcc, 25, v120
	s_and_b64 vcc, s[2:3], vcc
	s_nop 0
	v_cndmask_b32_e32 v94, v164, v94, vcc
	v_cmp_lt_i32_e32 vcc, 26, v120
	s_and_b64 vcc, s[2:3], vcc
	s_nop 0
	v_cndmask_b32_e32 v95, v164, v95, vcc
.LBB0_826:
	v_max3_f32 v120, v80, v81, v82
	v_max3_f32 v121, v83, v84, v85
	v_max3_f32 v122, v86, v87, v88
	v_max3_f32 v123, v89, v90, v91
	s_nop 0
	v_max3_f32 v120, v120, v92, v93
	v_max3_f32 v121, v121, v94, v95
	s_nop 0
	v_max3_f32 v120, v120, v121, v122
	s_nop 0
	v_max3_f32 v120, v120, v123, v123
	s_nop 0
	v_mov_b32_e32 v121, v120
	s_nop 1
	v_permlane32_swap_b32 v120, v121
	s_nop 0
	v_max_f32_e32 v121, v121, v121
	v_max_f32_e32 v120, v120, v120
	v_max_f32_e32 v120, v120, v121
	v_add_f32_e32 v120, v120, v248
	v_add_f32_e32 v121, 0x41000000, v118
	v_cmp_gt_f32_e32 vcc, v120, v121
	s_cbranch_vccz .LBB0_828
	v_max_f32_e32 v120, v120, v120
	v_max_f32_e32 v121, v118, v118
	v_max_f32_e32 v120, v121, v120
	v_sub_f32_e32 v118, v118, v120
	v_exp_f32_e32 v118, v118
	s_nop 0
	v_mul_f32_e32 v175, v175, v118
	v_pk_mul_f32 v[78:79], v[78:79], v[118:119] op_sel_hi:[1,0]
	v_pk_mul_f32 v[76:77], v[76:77], v[118:119] op_sel_hi:[1,0]
	v_pk_mul_f32 v[74:75], v[74:75], v[118:119] op_sel_hi:[1,0]
	v_pk_mul_f32 v[72:73], v[72:73], v[118:119] op_sel_hi:[1,0]
	v_pk_mul_f32 v[70:71], v[70:71], v[118:119] op_sel_hi:[1,0]
	v_pk_mul_f32 v[68:69], v[68:69], v[118:119] op_sel_hi:[1,0]
	v_pk_mul_f32 v[66:67], v[66:67], v[118:119] op_sel_hi:[1,0]
	v_pk_mul_f32 v[64:65], v[64:65], v[118:119] op_sel_hi:[1,0]
	v_pk_mul_f32 v[62:63], v[62:63], v[118:119] op_sel_hi:[1,0]
	v_pk_mul_f32 v[60:61], v[60:61], v[118:119] op_sel_hi:[1,0]
	v_pk_mul_f32 v[58:59], v[58:59], v[118:119] op_sel_hi:[1,0]
	v_pk_mul_f32 v[56:57], v[56:57], v[118:119] op_sel_hi:[1,0]
	v_pk_mul_f32 v[54:55], v[54:55], v[118:119] op_sel_hi:[1,0]
	v_pk_mul_f32 v[52:53], v[52:53], v[118:119] op_sel_hi:[1,0]
	v_pk_mul_f32 v[50:51], v[50:51], v[118:119] op_sel_hi:[1,0]
	v_pk_mul_f32 v[48:49], v[48:49], v[118:119] op_sel_hi:[1,0]
	v_mov_b32_e32 v118, v120
	v_cmp_lt_f32_e32 vcc, 0xdf0ac723, v118
	s_nop 1
	v_cndmask_b32_e32 v250, 0, v118, vcc
	v_sub_f32_e32 v251, v250, v248
	v_mov_b32_e32 v248, v250
	v_sub_f32_e32 v80, v80, v251
	v_sub_f32_e32 v81, v81, v251
	v_sub_f32_e32 v82, v82, v251
	v_sub_f32_e32 v83, v83, v251
	v_sub_f32_e32 v84, v84, v251
	v_sub_f32_e32 v85, v85, v251
	v_sub_f32_e32 v86, v86, v251
	v_sub_f32_e32 v87, v87, v251
	v_sub_f32_e32 v88, v88, v251
	v_sub_f32_e32 v89, v89, v251
	v_sub_f32_e32 v90, v90, v251
	v_sub_f32_e32 v91, v91, v251
	v_sub_f32_e32 v92, v92, v251
	v_sub_f32_e32 v93, v93, v251
	v_sub_f32_e32 v94, v94, v251
	v_sub_f32_e32 v95, v95, v251
; #define LAS __attribute__((address_space(3)))
; DI float fexp2(float x) { return __builtin_amdgcn_exp2f(x); }
; #define MFMA32(a, b, c) __builtin_amdgcn_mfma_f32_32x32x16_bf16((a), (b), (c), 0, 0, 0)
; template <int MODE>
; DI void nsa_tile(LAS const unsigned char* buf, const bf16x8 (&qf)[4], f32x16 (&o)[2], float& m, float& l, int kbase0, int t, bool lanesel, float slope2, int c, int hi) {
;     ...
;         const int klo = kbase0 + 32 * sub;
;         bool full, none;
;         if (MODE == 0) { full = lanesel && (klo + 31 <= t); none = !lanesel || (klo > t); }
;         else { full = (klo + 31 <= t) && (klo >= t - 511); none = (klo > t) || (klo + 31 < t - 511); }
;         if (__all(none)) continue;
;         int dbase = t - klo - 4 * hi;
;         asm volatile("" : "+v"(dbase));
;         const float b0 = none ? -1e30f : -slope2 * (float)dbase;
;         f32x16 s;
; #pragma unroll
;         for (int i = 0; i < 16; ++i) s[i] = fmaf(slope2, (float)((i & 3) + 8 * (i >> 2)), b0);
; #pragma unroll
;         for (int st = 0; st < 4; ++st) {
;             const bf16x8 a = *(LAS const bf16x8*)(buf + (32 * sub + c) * 144 + st * 32 + hi * 16);
;             s = MFMA32(a, qf[st], s);
;         }
;         if (__any(!full && !none)) {
; #pragma unroll
;             for (int i = 0; i < 16; ++i) {
;                 const int dist = dbase - ((i & 3) + 8 * (i >> 2));
;                 const bool valid = (MODE == 0) ? (lanesel && dist >= 0) : ((unsigned)dist < 512u);
;                 if (!valid) s[i] = -1e30f;
;             }
;         }
;     ...
;         float ps = 0.f;
; #pragma unroll
;         for (int i = 0; i < 16; ++i) { const float pv = fexp2(s[i] - m); s[i] = pv; ps += pv; }
;         l += ps;
;         const bf16x8 pb0 = packp(s, 0), pb1 = packp(s, 1);
; #pragma unroll
;         for (int db = 0; db < 2; ++db)
; #pragma unroll
;             for (int tt = 0; tt < 2; ++tt) {
;                 LAS const unsigned char* ap = buf + 9216 + (32 * db + c) * 136 + (32 * sub + 16 * tt + 4 * hi) * 2;
;                 const bf16x8 a = cat4(*(LAS const bf16x4*)ap, *(LAS const bf16x4*)(ap + 16));
;                 o[db] = MFMA32(a, tt == 0 ? pb0 : pb1, o[db]);
;             }
.LBB0_828:
	v_exp_f32_e32 v80, v80
	v_exp_f32_e32 v81, v81
	v_exp_f32_e32 v82, v82
	v_exp_f32_e32 v83, v83
	v_add_f32_e32 v120, 0, v80
	v_exp_f32_e32 v121, v84
	v_add_f32_e32 v120, v81, v120
	v_add_f32_e32 v120, v82, v120
	v_add_f32_e32 v120, v83, v120
	v_add_f32_e32 v84, v121, v120
	v_exp_f32_e32 v120, v85
	v_exp_f32_e32 v122, v86
	v_exp_f32_e32 v87, v87
	v_exp_f32_e32 v88, v88
	v_add_f32_e32 v84, v120, v84
	v_exp_f32_e32 v89, v89
	v_add_f32_e32 v84, v122, v84
	v_exp_f32_e32 v90, v90
	v_add_f32_e32 v84, v87, v84
	v_exp_f32_e32 v91, v91
	v_add_f32_e32 v84, v88, v84
	v_exp_f32_e32 v92, v92
	v_add_f32_e32 v84, v89, v84
	v_exp_f32_e32 v93, v93
	v_add_f32_e32 v84, v90, v84
	v_exp_f32_e32 v94, v94
	v_add_f32_e32 v84, v91, v84
	v_exp_f32_e32 v95, v95
	v_add_f32_e32 v84, v92, v84
	v_add_f32_e32 v84, v93, v84
	v_add_f32_e32 v84, v94, v84
	v_cvt_pk_bf16_f32 v86, v121, v120
	v_add3_u32 v120, s14, v15, v174
	v_add_f32_e32 v84, v95, v84
	v_cvt_pk_bf16_f32 v85, v82, v83
	v_cvt_pk_bf16_f32 v82, v92, v93
	v_add_u32_e32 v92, 0x2000, v120
	v_add_f32_e32 v175, v175, v84
	v_cvt_pk_bf16_f32 v84, v80, v81
	v_cvt_pk_bf16_f32 v80, v88, v89
	v_cvt_pk_bf16_f32 v81, v90, v91
	v_cvt_pk_bf16_f32 v83, v94, v95
	ds_read2_b64 v[88:91], v92 offset0:128 offset1:130
	ds_read2_b64 v[92:95], v92 offset0:132 offset1:134
	v_cvt_pk_bf16_f32 v87, v122, v87
	s_waitcnt lgkmcnt(1)
	s_nop 0
	v_mfma_f32_32x32x16_bf16 v[48:63], v[88:91], v[84:87], v[48:63]
	s_waitcnt lgkmcnt(0)
	v_mfma_f32_32x32x16_bf16 v[48:63], v[92:95], v[80:83], v[48:63]
	v_add_u32_e32 v92, 0x3000, v120
	ds_read2_b64 v[88:91], v92 offset0:160 offset1:162
	s_waitcnt lgkmcnt(0)
	v_mfma_f32_32x32x16_bf16 v[64:79], v[88:91], v[84:87], v[64:79]
	ds_read2_b64 v[84:87], v92 offset0:164 offset1:166
	s_waitcnt lgkmcnt(0)
	v_mfma_f32_32x32x16_bf16 v[64:79], v[84:87], v[80:83], v[64:79]
.LBB0_829:
	s_or_b32 s16, s15, 32
	v_cmp_gt_i32_e32 vcc, s16, v150
	s_or_b64 vcc, s[6:7], vcc
	s_nop 0
	v_cndmask_b32_e64 v80, 0, 1, vcc
	v_cmp_ne_u32_e64 s[4:5], 0, v80
	s_cmp_eq_u64 s[4:5], exec
	s_cbranch_scc1 .LBB0_835
	v_subrev_u32_e32 v120, s16, v117
	ds_read_b128 v[122:125], v119 offset:4608
	v_cvt_f32_i32_e32 v80, v120
	s_or_b32 s4, s15, 63
	v_cmp_gt_i32_e64 s[4:5], s4, v150
	s_xor_b64 s[6:7], vcc, -1
	v_mul_f32_e64 v80, -v152, v80
	v_cndmask_b32_e32 v94, v80, v164, vcc
	v_sub_f32_e32 v94, v94, v248
	v_fma_f32 v80, 0, v152, v94
	v_add_f32_e32 v81, v152, v94
	v_pk_fma_f32 v[82:83], v[152:153], s[72:73], v[94:95] op_sel_hi:[1,1,0]
	v_pk_fma_f32 v[84:85], v[152:153], s[74:75], v[94:95] op_sel_hi:[1,1,0]
	v_pk_fma_f32 v[86:87], v[152:153], s[76:77], v[94:95] op_sel_hi:[1,1,0]
	v_pk_fma_f32 v[88:89], v[152:153], s[70:71], v[94:95] op_sel_hi:[1,1,0]
	v_pk_fma_f32 v[90:91], v[152:153], s[78:79], v[94:95] op_sel_hi:[1,1,0]
	v_pk_fma_f32 v[92:93], v[152:153], s[80:81], v[94:95] op_sel_hi:[1,1,0]
	v_pk_fma_f32 v[94:95], v[152:153], s[82:83], v[94:95] op_sel_hi:[1,1,0]
	s_and_b64 s[4:5], s[6:7], s[4:5]
	s_waitcnt lgkmcnt(0)
	v_mfma_f32_32x32x16_bf16 v[80:95], v[122:125], v[128:131], v[80:95]
	ds_read_b128 v[122:125], v119 offset:4640
	s_waitcnt lgkmcnt(0)
	v_mfma_f32_32x32x16_bf16 v[80:95], v[122:125], v[132:135], v[80:95]
	ds_read_b128 v[122:125], v119 offset:4672
	s_waitcnt lgkmcnt(0)
	v_mfma_f32_32x32x16_bf16 v[80:95], v[122:125], v[136:139], v[80:95]
	ds_read_b128 v[122:125], v119 offset:4704
	v_cndmask_b32_e64 v119, 0, 1, s[4:5]
	v_cmp_ne_u32_e32 vcc, 0, v119
	s_waitcnt lgkmcnt(0)
	v_mfma_f32_32x32x16_bf16 v[80:95], v[122:125], v[140:143], v[80:95]
	s_cbranch_vccz .LBB0_832
	v_cmp_lt_i32_e32 vcc, -1, v120
	s_and_b64 vcc, s[2:3], vcc
	s_nop 8
	v_cndmask_b32_e32 v80, v164, v80, vcc
	v_cmp_lt_i32_e32 vcc, 0, v120
	s_and_b64 vcc, s[2:3], vcc
	s_nop 0
	v_cndmask_b32_e32 v81, v164, v81, vcc
	v_cmp_lt_i32_e32 vcc, 1, v120
	s_and_b64 vcc, s[2:3], vcc
	s_nop 0
	v_cndmask_b32_e32 v82, v164, v82, vcc
	v_cmp_lt_i32_e32 vcc, 2, v120
	s_and_b64 vcc, s[2:3], vcc
	s_nop 0
	v_cndmask_b32_e32 v83, v164, v83, vcc
	v_cmp_lt_i32_e32 vcc, 7, v120
	s_and_b64 vcc, s[2:3], vcc
	s_nop 0
	v_cndmask_b32_e32 v84, v164, v84, vcc
	v_cmp_lt_i32_e32 vcc, 8, v120
	s_and_b64 vcc, s[2:3], vcc
	s_nop 0
	v_cndmask_b32_e32 v85, v164, v85, vcc
	v_cmp_lt_i32_e32 vcc, 9, v120
	s_and_b64 vcc, s[2:3], vcc
	s_nop 0
	v_cndmask_b32_e32 v86, v164, v86, vcc
	v_cmp_lt_i32_e32 vcc, 10, v120
	s_and_b64 vcc, s[2:3], vcc
	s_nop 0
	v_cndmask_b32_e32 v87, v164, v87, vcc
	v_cmp_lt_i32_e32 vcc, 15, v120
	s_and_b64 vcc, s[2:3], vcc
	s_nop 0
	v_cndmask_b32_e32 v88, v164, v88, vcc
	v_cmp_lt_i32_e32 vcc, 16, v120
	s_and_b64 vcc, s[2:3], vcc
	s_nop 0
	v_cndmask_b32_e32 v89, v164, v89, vcc
	v_cmp_lt_i32_e32 vcc, 17, v120
	s_and_b64 vcc, s[2:3], vcc
	s_nop 0
	v_cndmask_b32_e32 v90, v164, v90, vcc
	v_cmp_lt_i32_e32 vcc, 18, v120
	s_and_b64 vcc, s[2:3], vcc
	s_nop 0
	v_cndmask_b32_e32 v91, v164, v91, vcc
	v_cmp_lt_i32_e32 vcc, 23, v120
	s_and_b64 vcc, s[2:3], vcc
	s_nop 0
	v_cndmask_b32_e32 v92, v164, v92, vcc
	v_cmp_lt_i32_e32 vcc, 24, v120
	s_and_b64 vcc, s[2:3], vcc
	s_nop 0
	v_cndmask_b32_e32 v93, v164, v93, vcc
	v_cmp_lt_i32_e32 vcc, 25, v120
	s_and_b64 vcc, s[2:3], vcc
	s_nop 0
	v_cndmask_b32_e32 v94, v164, v94, vcc
	v_cmp_lt_i32_e32 vcc, 26, v120
	s_and_b64 vcc, s[2:3], vcc
	s_nop 0
	v_cndmask_b32_e32 v95, v164, v95, vcc
; #define LAS __attribute__((address_space(3)))
; DI float xhalf_max(float v) { unsigned a = __builtin_bit_cast(unsigned, v), b = a; swap32(a, b); return fmaxf(__builtin_bit_cast(float, a), __builtin_bit_cast(float, b)); }
; DI float fexp2(float x) { return __builtin_amdgcn_exp2f(x); }
; #define MFMA32(a, b, c) __builtin_amdgcn_mfma_f32_32x32x16_bf16((a), (b), (c), 0, 0, 0)
; template <int MODE>
; DI void nsa_tile(LAS const unsigned char* buf, const bf16x8 (&qf)[4], f32x16 (&o)[2], float& m, float& l, int kbase0, int t, bool lanesel, float slope2, int c, int hi) {
;     ...
;         float mx = max16(s);
;         mx = xhalf_max(mx);
;         if (__any(mx > m + 8.f)) {
;             const float mn = fmaxf(m, mx), alpha = fexp2(m - mn); m = mn; l *= alpha;
;             o[0] = o[0] * alpha; o[1] = o[1] * alpha;
;         }
;         float ps = 0.f;
; #pragma unroll
;         for (int i = 0; i < 16; ++i) { const float pv = fexp2(s[i] - m); s[i] = pv; ps += pv; }
;         l += ps;
;         const bf16x8 pb0 = packp(s, 0), pb1 = packp(s, 1);
; #pragma unroll
;         for (int db = 0; db < 2; ++db)
; #pragma unroll
;             for (int tt = 0; tt < 2; ++tt) {
;                 LAS const unsigned char* ap = buf + 9216 + (32 * db + c) * 136 + (32 * sub + 16 * tt + 4 * hi) * 2;
;                 const bf16x8 a = cat4(*(LAS const bf16x4*)ap, *(LAS const bf16x4*)(ap + 16));
;                 o[db] = MFMA32(a, tt == 0 ? pb0 : pb1, o[db]);
;             }
.LBB0_832:
	v_max3_f32 v119, v80, v81, v82
	v_max3_f32 v120, v83, v84, v85
	v_max3_f32 v121, v86, v87, v88
	v_max3_f32 v122, v89, v90, v91
	s_nop 0
	v_max3_f32 v119, v119, v92, v93
	v_max3_f32 v120, v120, v94, v95
	s_nop 0
	v_max3_f32 v119, v119, v120, v121
	s_nop 0
	v_max3_f32 v119, v119, v122, v122
	s_nop 0
	v_mov_b32_e32 v120, v119
	s_nop 1
	v_permlane32_swap_b32 v119, v120
	s_nop 0
	v_max_f32_e32 v120, v120, v120
	v_max_f32_e32 v119, v119, v119
	v_max_f32_e32 v119, v119, v120
	v_add_f32_e32 v119, v119, v248
	v_add_f32_e32 v120, 0x41000000, v118
	v_cmp_gt_f32_e32 vcc, v119, v120
	s_cbranch_vccz .LBB0_834
	v_max_f32_e32 v119, v119, v119
	v_max_f32_e32 v120, v118, v118
	v_max_f32_e32 v119, v120, v119
	v_sub_f32_e32 v118, v118, v119
	v_exp_f32_e32 v118, v118
	s_nop 0
	v_mul_f32_e32 v175, v175, v118
	v_pk_mul_f32 v[78:79], v[78:79], v[118:119] op_sel_hi:[1,0]
	v_pk_mul_f32 v[76:77], v[76:77], v[118:119] op_sel_hi:[1,0]
	v_pk_mul_f32 v[74:75], v[74:75], v[118:119] op_sel_hi:[1,0]
	v_pk_mul_f32 v[72:73], v[72:73], v[118:119] op_sel_hi:[1,0]
	v_pk_mul_f32 v[70:71], v[70:71], v[118:119] op_sel_hi:[1,0]
	v_pk_mul_f32 v[68:69], v[68:69], v[118:119] op_sel_hi:[1,0]
	v_pk_mul_f32 v[66:67], v[66:67], v[118:119] op_sel_hi:[1,0]
	v_pk_mul_f32 v[64:65], v[64:65], v[118:119] op_sel_hi:[1,0]
	v_pk_mul_f32 v[62:63], v[62:63], v[118:119] op_sel_hi:[1,0]
	v_pk_mul_f32 v[60:61], v[60:61], v[118:119] op_sel_hi:[1,0]
	v_pk_mul_f32 v[58:59], v[58:59], v[118:119] op_sel_hi:[1,0]
	v_pk_mul_f32 v[56:57], v[56:57], v[118:119] op_sel_hi:[1,0]
	v_pk_mul_f32 v[54:55], v[54:55], v[118:119] op_sel_hi:[1,0]
	v_pk_mul_f32 v[52:53], v[52:53], v[118:119] op_sel_hi:[1,0]
	v_pk_mul_f32 v[50:51], v[50:51], v[118:119] op_sel_hi:[1,0]
	v_pk_mul_f32 v[48:49], v[48:49], v[118:119] op_sel_hi:[1,0]
	v_mov_b32_e32 v118, v119
	v_cmp_lt_f32_e32 vcc, 0xdf0ac723, v118
	s_nop 1
	v_cndmask_b32_e32 v250, 0, v118, vcc
	v_sub_f32_e32 v251, v250, v248
	v_mov_b32_e32 v248, v250
	v_sub_f32_e32 v80, v80, v251
	v_sub_f32_e32 v81, v81, v251
	v_sub_f32_e32 v82, v82, v251
	v_sub_f32_e32 v83, v83, v251
	v_sub_f32_e32 v84, v84, v251
	v_sub_f32_e32 v85, v85, v251
	v_sub_f32_e32 v86, v86, v251
	v_sub_f32_e32 v87, v87, v251
	v_sub_f32_e32 v88, v88, v251
	v_sub_f32_e32 v89, v89, v251
	v_sub_f32_e32 v90, v90, v251
	v_sub_f32_e32 v91, v91, v251
	v_sub_f32_e32 v92, v92, v251
	v_sub_f32_e32 v93, v93, v251
	v_sub_f32_e32 v94, v94, v251
	v_sub_f32_e32 v95, v95, v251
.LBB0_834:
	v_exp_f32_e32 v119, v80
	v_exp_f32_e32 v120, v81
	v_exp_f32_e32 v121, v82
	v_exp_f32_e32 v122, v83
	v_add_f32_e32 v80, 0, v119
	v_add_f32_e32 v80, v120, v80
	v_add_f32_e32 v80, v121, v80
	v_add_f32_e32 v123, v122, v80
	v_exp_f32_e32 v124, v84
	v_exp_f32_e32 v125, v85
	v_exp_f32_e32 v126, v86
	v_exp_f32_e32 v127, v87
	v_exp_f32_e32 v144, v88
	v_exp_f32_e32 v145, v89
	v_exp_f32_e32 v146, v90
	v_exp_f32_e32 v147, v91
	v_exp_f32_e32 v154, v92
	v_exp_f32_e32 v156, v93
	v_add3_u32 v80, s14, v15, v174
	v_add_u32_e32 v88, 0x2000, v80
	ds_read2_b64 v[80:83], v88 offset0:136 offset1:138
	v_exp_f32_e32 v157, v94
	v_exp_f32_e32 v158, v95
	v_cvt_pk_bf16_f32 v84, v119, v120
	v_cvt_pk_bf16_f32 v85, v121, v122
	v_cvt_pk_bf16_f32 v86, v124, v125
	v_cvt_pk_bf16_f32 v87, v126, v127
	ds_read2_b64 v[88:91], v88 offset0:140 offset1:142
	v_add3_u32 v92, s14, v176, v174
	s_waitcnt lgkmcnt(1)
	v_mfma_f32_32x32x16_bf16 v[48:63], v[80:83], v[84:87], v[48:63]
	v_add_u32_e32 v119, 0x2000, v92
	ds_read2_b64 v[92:95], v119 offset0:136 offset1:138
	v_cvt_pk_bf16_f32 v80, v144, v145
	v_cvt_pk_bf16_f32 v81, v146, v147
	v_cvt_pk_bf16_f32 v82, v154, v156
	v_cvt_pk_bf16_f32 v83, v157, v158
	s_waitcnt lgkmcnt(0)
	v_mfma_f32_32x32x16_bf16 v[64:79], v[92:95], v[84:87], v[64:79]
	v_mfma_f32_32x32x16_bf16 v[48:63], v[88:91], v[80:83], v[48:63]
	v_add_f32_e32 v88, v124, v123
	v_add_f32_e32 v88, v125, v88
	v_add_f32_e32 v88, v126, v88
	v_add_f32_e32 v88, v127, v88
	v_add_f32_e32 v88, v144, v88
	v_add_f32_e32 v120, v145, v88
	ds_read2_b64 v[88:91], v119 offset0:140 offset1:142
	s_waitcnt lgkmcnt(0)
	v_mfma_f32_32x32x16_bf16 v[64:79], v[88:91], v[80:83], v[64:79]
	v_add_f32_e32 v84, v146, v120
	v_add_f32_e32 v84, v147, v84
	v_add_f32_e32 v84, v154, v84
	v_add_f32_e32 v84, v156, v84
	v_add_f32_e32 v84, v157, v84
	v_add_f32_e32 v84, v158, v84
	v_add_f32_e32 v175, v175, v84

; #define LAS __attribute__((address_space(3)))
; #define ST_V(base, v) do { LAS unsigned char* vp_ = (base) + voff; *(LAS u32x2*)vp_ = (u32x2){(v).x, (v).y}; *(LAS u32x2*)(vp_ + 8) = (u32x2){(v).z, (v).w}; } while (0)
; DI void nsa_unit(const Params& p, LAS unsigned char* lds, unsigned char* ldsg, int bg, int qt, int tid) {
;     ...
;     {
;         const int lo_key = (q0 - 511 > 0) ? (q0 - 511) : 0;
;         const int kt_lo = lo_key >> 6, kt_hi = (q0 + 31) >> 6;
;         const bf16_t* Ksrc = PROJ + (tokb + kq) * NPROJ + 2368 + g * 64 + 8 * kch;
;         const bf16_t* Vsrc = VWT + ((size_t)(bg * 64 + kq)) * S_ + 8 * kch;
;         f32x16 o[2];
; #pragma unroll
;         for (int db = 0; db < 2; ++db)
; #pragma unroll
;             for (int i = 0; i < 16; ++i) o[db][i] = 0.f;
;         float m = -1e20f, l = 0.f;
;         u32x4 rk1, rv1, rk2, rv2;
;         rk1 = *(const u32x4*)(Ksrc + (size_t)(64 * kt_lo) * NPROJ); rv1 = *(const u32x4*)(Vsrc + 64 * kt_lo);
;         *(LAS u32x4*)(lds + toff) = rk1; ST_V(lds, rv1);
;         if (kt_lo < kt_hi) { rk1 = *(const u32x4*)(Ksrc + (size_t)(64 * (kt_lo + 1)) * NPROJ); rv1 = *(const u32x4*)(Vsrc + 64 * (kt_lo + 1)); }
;         __syncthreads();
;         int cb = 0;
.LBB0_842:
	s_cmp_le_u32 s7, s6
	s_mov_b64 s[2:3], -1
	s_waitcnt lgkmcnt(0)
	s_barrier
	s_cbranch_scc0 .LBB0_863
	v_lshlrev_b32_e32 v154, 2, v114
	s_add_i32 s2, s84, 0xfffffe01
	v_sub_u32_e32 v10, v115, v154
	s_and_b32 s8, s2, 0xffffffc0
	s_movk_i32 s2, 0x88
	v_subrev_u32_e32 v10, s56, v10
	v_mov_b32_e32 v94, v1
	v_mov_b32_e32 v95, v1
	v_mad_u64_u32 v[160:161], s[2:3], v116, s2, v[112:113]
	v_subrev_u32_e32 v10, s8, v10
	v_mov_b32_e32 v80, v1
	v_mov_b32_e32 v81, v1
	v_mov_b32_e32 v82, v1
	v_mov_b32_e32 v83, v1
	v_mov_b32_e32 v84, v1
	v_mov_b32_e32 v85, v1
	v_mov_b32_e32 v86, v1
	v_mov_b32_e32 v87, v1
	v_mov_b32_e32 v88, v1
	v_mov_b32_e32 v89, v1
	v_mov_b32_e32 v90, v1
	v_mov_b32_e32 v91, v1
	v_mov_b32_e32 v92, v1
	v_mov_b32_e32 v93, v1
	v_mov_b64_e32 v[110:111], v[94:95]
	s_addk_i32 s40, 0xfe01
	v_add_u32_e32 v178, 0xfffffe01, v150
	v_mov_b32_e32 v153, v152
	v_add_u32_e32 v179, 0x1fc0, v10
	s_mov_b32 s9, 0
	v_mov_b32_e32 v180, 0xe0ad78ec
	v_mov_b32_e32 v249, 0
	v_mov_b32_e32 v161, 0
	v_mov_b64_e32 v[108:109], v[92:93]
	v_mov_b64_e32 v[106:107], v[90:91]
	v_mov_b64_e32 v[104:105], v[88:89]
	v_mov_b64_e32 v[102:103], v[86:87]
	v_mov_b64_e32 v[100:101], v[84:85]
	v_mov_b64_e32 v[98:99], v[82:83]
	v_mov_b64_e32 v[96:97], v[80:81]
	s_add_i32 s2, s7, 2
	s_cmp_gt_u32 s2, s6
	s_cbranch_scc1 .LBB0_846
	s_branch .LBB0_845

; #define LAS __attribute__((address_space(3)))
; DI float xhalf_max(float v) { unsigned a = __builtin_bit_cast(unsigned, v), b = a; swap32(a, b); return fmaxf(__builtin_bit_cast(float, a), __builtin_bit_cast(float, b)); }
; DI float fexp2(float x) { return __builtin_amdgcn_exp2f(x); }
; #define MFMA32(a, b, c) __builtin_amdgcn_mfma_f32_32x32x16_bf16((a), (b), (c), 0, 0, 0)
; template <int MODE>
; DI void nsa_tile(LAS const unsigned char* buf, const bf16x8 (&qf)[4], f32x16 (&o)[2], float& m, float& l, int kbase0, int t, bool lanesel, float slope2, int c, int hi) {
;     ...
;     for (int sub = 0; sub < 2; ++sub) {
;         const int klo = kbase0 + 32 * sub;
;         bool full, none;
;         if (MODE == 0) { full = lanesel && (klo + 31 <= t); none = !lanesel || (klo > t); }
;         else { full = (klo + 31 <= t) && (klo >= t - 511); none = (klo > t) || (klo + 31 < t - 511); }
;         if (__all(none)) continue;
;         int dbase = t - klo - 4 * hi;
;         asm volatile("" : "+v"(dbase));
;         const float b0 = none ? -1e30f : -slope2 * (float)dbase;
;         f32x16 s;
; #pragma unroll
;         for (int i = 0; i < 16; ++i) s[i] = fmaf(slope2, (float)((i & 3) + 8 * (i >> 2)), b0);
; #pragma unroll
;         for (int st = 0; st < 4; ++st) {
;             const bf16x8 a = *(LAS const bf16x8*)(buf + (32 * sub + c) * 144 + st * 32 + hi * 16);
;             s = MFMA32(a, qf[st], s);
;         }
;         if (__any(!full && !none)) {
; #pragma unroll
;             for (int i = 0; i < 16; ++i) {
;                 const int dist = dbase - ((i & 3) + 8 * (i >> 2));
;                 const bool valid = (MODE == 0) ? (lanesel && dist >= 0) : ((unsigned)dist < 512u);
;                 if (!valid) s[i] = -1e30f;
;             }
;         }
;         float mx = max16(s);
;         mx = xhalf_max(mx);
;         if (__any(mx > m + 8.f)) {
;             const float mn = fmaxf(m, mx), alpha = fexp2(m - mn); m = mn; l *= alpha;
;             o[0] = o[0] * alpha; o[1] = o[1] * alpha;
;         }
.LBB0_846:
	s_add_i32 s11, s8, 63
	s_cmp_lt_i32 s11, s40
	s_cselect_b64 s[2:3], -1, 0
	s_cmp_gt_i32 s8, s55
	s_cselect_b64 s[4:5], -1, 0
	s_or_b64 s[2:3], s[4:5], s[2:3]
	s_and_b64 vcc, exec, s[2:3]
	s_cbranch_vccnz .LBB0_859
	s_mul_i32 s2, s9, 0x4600
	s_add_i32 s4, s8, 31
	s_add_i32 s10, s2, 0
	v_cmp_gt_i32_e32 vcc, s8, v150
	v_cmp_lt_i32_e64 s[2:3], s4, v178
	s_or_b64 vcc, vcc, s[2:3]
	v_cndmask_b32_e64 v113, 0, 1, vcc
	v_add_u32_e32 v112, s10, v0
	v_cmp_ne_u32_e64 s[2:3], 0, v113
	s_cmp_eq_u64 s[2:3], exec
	v_add_u32_e32 v181, v112, v171
	s_cbranch_scc1 .LBB0_853
	v_add_u32_e32 v182, 32, v179
	ds_read_b128 v[184:187], v181
	v_cvt_f32_i32_e32 v112, v182
	v_cmp_gt_i32_e64 s[2:3], s4, v150
	v_cmp_lt_i32_e64 s[4:5], s8, v178
	s_or_b64 s[2:3], s[2:3], s[4:5]
	v_mul_f32_e64 v112, -v152, v112
	v_cndmask_b32_e32 v126, v112, v164, vcc
	v_sub_f32_e32 v126, v126, v249
	v_fma_f32 v112, 0, v152, v126
	v_add_f32_e32 v113, v152, v126
	v_pk_fma_f32 v[114:115], v[152:153], s[72:73], v[126:127] op_sel_hi:[1,1,0]
	v_pk_fma_f32 v[116:117], v[152:153], s[74:75], v[126:127] op_sel_hi:[1,1,0]
	v_pk_fma_f32 v[118:119], v[152:153], s[76:77], v[126:127] op_sel_hi:[1,1,0]
	v_pk_fma_f32 v[120:121], v[152:153], s[70:71], v[126:127] op_sel_hi:[1,1,0]
	v_pk_fma_f32 v[122:123], v[152:153], s[78:79], v[126:127] op_sel_hi:[1,1,0]
	v_pk_fma_f32 v[124:125], v[152:153], s[80:81], v[126:127] op_sel_hi:[1,1,0]
	v_pk_fma_f32 v[126:127], v[152:153], s[82:83], v[126:127] op_sel_hi:[1,1,0]
	s_xor_b64 s[4:5], vcc, -1
	s_and_b64 s[2:3], s[2:3], s[4:5]
	s_waitcnt lgkmcnt(0)
	v_mfma_f32_32x32x16_bf16 v[112:127], v[184:187], v[128:131], v[112:127]
	ds_read_b128 v[184:187], v181 offset:32
	v_cndmask_b32_e64 v183, 0, 1, s[2:3]
	v_cmp_ne_u32_e32 vcc, 0, v183
	s_waitcnt lgkmcnt(0)
	v_mfma_f32_32x32x16_bf16 v[112:127], v[184:187], v[132:135], v[112:127]
	ds_read_b128 v[184:187], v181 offset:64
	s_waitcnt lgkmcnt(0)
	v_mfma_f32_32x32x16_bf16 v[112:127], v[184:187], v[136:139], v[112:127]
	ds_read_b128 v[184:187], v181 offset:96
	s_waitcnt lgkmcnt(0)
	v_mfma_f32_32x32x16_bf16 v[112:127], v[184:187], v[140:143], v[112:127]
	s_cbranch_vccz .LBB0_850
	v_cmp_gt_u32_e32 vcc, s89, v182
	v_add_u32_e32 v183, -1, v182
	s_nop 8
	v_cndmask_b32_e32 v112, v164, v112, vcc
	v_cmp_gt_u32_e32 vcc, s89, v183
	v_add_u32_e32 v183, -2, v182
	s_nop 0
	v_cndmask_b32_e32 v113, v164, v113, vcc
	v_cmp_gt_u32_e32 vcc, s89, v183
	v_add_u32_e32 v183, -3, v182
	s_nop 0
	v_cndmask_b32_e32 v114, v164, v114, vcc
	v_cmp_gt_u32_e32 vcc, s89, v183
	v_add_u32_e32 v183, -8, v182
	s_nop 0
	v_cndmask_b32_e32 v115, v164, v115, vcc
	v_cmp_gt_u32_e32 vcc, s89, v183
	v_add_u32_e32 v183, -9, v182
	s_nop 0
	v_cndmask_b32_e32 v116, v164, v116, vcc
	v_cmp_gt_u32_e32 vcc, s89, v183
	v_add_u32_e32 v183, -10, v182
	s_nop 0
	v_cndmask_b32_e32 v117, v164, v117, vcc
	v_cmp_gt_u32_e32 vcc, s89, v183
	v_add_u32_e32 v183, -11, v182
	s_nop 0
	v_cndmask_b32_e32 v118, v164, v118, vcc
	v_cmp_gt_u32_e32 vcc, s89, v183
	v_add_u32_e32 v183, -16, v182
	s_nop 0
	v_cndmask_b32_e32 v119, v164, v119, vcc
	v_cmp_gt_u32_e32 vcc, s89, v183
	v_subrev_u32_e32 v183, 17, v182
	s_nop 0
	v_cndmask_b32_e32 v120, v164, v120, vcc
	v_cmp_gt_u32_e32 vcc, s89, v183
	v_subrev_u32_e32 v183, 18, v182
	s_nop 0
	v_cndmask_b32_e32 v121, v164, v121, vcc
	v_cmp_gt_u32_e32 vcc, s89, v183
	v_subrev_u32_e32 v183, 19, v182
	s_nop 0
	v_cndmask_b32_e32 v122, v164, v122, vcc
	v_cmp_gt_u32_e32 vcc, s89, v183
	v_subrev_u32_e32 v183, 24, v182
	s_nop 0
	v_cndmask_b32_e32 v123, v164, v123, vcc
	v_cmp_gt_u32_e32 vcc, s89, v183
	v_subrev_u32_e32 v183, 25, v182
	s_nop 0
	v_cndmask_b32_e32 v124, v164, v124, vcc
	v_cmp_gt_u32_e32 vcc, s89, v183
	v_subrev_u32_e32 v183, 26, v182
	v_subrev_u32_e32 v182, 27, v182
	v_cndmask_b32_e32 v125, v164, v125, vcc
	v_cmp_gt_u32_e32 vcc, s89, v183
	s_nop 1
	v_cndmask_b32_e32 v126, v164, v126, vcc
	v_cmp_gt_u32_e32 vcc, s89, v182
	s_nop 1
	v_cndmask_b32_e32 v127, v164, v127, vcc
.LBB0_850:
	v_max3_f32 v182, v112, v113, v114
	v_max3_f32 v183, v115, v116, v117
	v_max3_f32 v184, v118, v119, v120
	v_max3_f32 v185, v121, v122, v123
	s_nop 0
	v_max3_f32 v182, v182, v124, v125
	v_max3_f32 v183, v183, v126, v127
	s_nop 0
	v_max3_f32 v182, v182, v183, v184
	s_nop 0
	v_max3_f32 v182, v182, v185, v185
	s_nop 0
	v_mov_b32_e32 v183, v182
	s_nop 1
	v_permlane32_swap_b32 v182, v183
	s_nop 0
	v_max_f32_e32 v183, v183, v183
	v_max_f32_e32 v182, v182, v182
	v_max_f32_e32 v182, v182, v183
	v_add_f32_e32 v182, v182, v249
	v_add_f32_e32 v183, 0x41000000, v180
	v_cmp_gt_f32_e32 vcc, v182, v183
	s_cbranch_vccz .LBB0_852
	v_max_f32_e32 v182, v182, v182
	v_max_f32_e32 v183, v180, v180
	v_max_f32_e32 v182, v183, v182
	v_sub_f32_e32 v180, v180, v182
	v_exp_f32_e32 v180, v180
	s_nop 0
	v_mul_f32_e32 v161, v161, v180
	v_pk_mul_f32 v[110:111], v[110:111], v[180:181] op_sel_hi:[1,0]
	v_pk_mul_f32 v[108:109], v[108:109], v[180:181] op_sel_hi:[1,0]
	v_pk_mul_f32 v[106:107], v[106:107], v[180:181] op_sel_hi:[1,0]
	v_pk_mul_f32 v[104:105], v[104:105], v[180:181] op_sel_hi:[1,0]
	v_pk_mul_f32 v[102:103], v[102:103], v[180:181] op_sel_hi:[1,0]
	v_pk_mul_f32 v[100:101], v[100:101], v[180:181] op_sel_hi:[1,0]
	v_pk_mul_f32 v[98:99], v[98:99], v[180:181] op_sel_hi:[1,0]
	v_pk_mul_f32 v[96:97], v[96:97], v[180:181] op_sel_hi:[1,0]
	v_pk_mul_f32 v[94:95], v[94:95], v[180:181] op_sel_hi:[1,0]
	v_pk_mul_f32 v[92:93], v[92:93], v[180:181] op_sel_hi:[1,0]
	v_pk_mul_f32 v[90:91], v[90:91], v[180:181] op_sel_hi:[1,0]
	v_pk_mul_f32 v[88:89], v[88:89], v[180:181] op_sel_hi:[1,0]
	v_pk_mul_f32 v[86:87], v[86:87], v[180:181] op_sel_hi:[1,0]
	v_pk_mul_f32 v[84:85], v[84:85], v[180:181] op_sel_hi:[1,0]
	v_pk_mul_f32 v[82:83], v[82:83], v[180:181] op_sel_hi:[1,0]
	v_pk_mul_f32 v[80:81], v[80:81], v[180:181] op_sel_hi:[1,0]
	v_mov_b32_e32 v180, v182
	v_cmp_lt_f32_e32 vcc, 0xdf0ac723, v180
	s_nop 1
	v_cndmask_b32_e32 v250, 0, v180, vcc
	v_sub_f32_e32 v251, v250, v249
	v_mov_b32_e32 v249, v250
	v_sub_f32_e32 v112, v112, v251
	v_sub_f32_e32 v113, v113, v251
	v_sub_f32_e32 v114, v114, v251
	v_sub_f32_e32 v115, v115, v251
	v_sub_f32_e32 v116, v116, v251
	v_sub_f32_e32 v117, v117, v251
	v_sub_f32_e32 v118, v118, v251
	v_sub_f32_e32 v119, v119, v251
	v_sub_f32_e32 v120, v120, v251
	v_sub_f32_e32 v121, v121, v251
	v_sub_f32_e32 v122, v122, v251
	v_sub_f32_e32 v123, v123, v251
	v_sub_f32_e32 v124, v124, v251
	v_sub_f32_e32 v125, v125, v251
	v_sub_f32_e32 v126, v126, v251
	v_sub_f32_e32 v127, v127, v251
; #define LAS __attribute__((address_space(3)))
; DI float fexp2(float x) { return __builtin_amdgcn_exp2f(x); }
; #define MFMA32(a, b, c) __builtin_amdgcn_mfma_f32_32x32x16_bf16((a), (b), (c), 0, 0, 0)
; template <int MODE>
; DI void nsa_tile(LAS const unsigned char* buf, const bf16x8 (&qf)[4], f32x16 (&o)[2], float& m, float& l, int kbase0, int t, bool lanesel, float slope2, int c, int hi) {
;     ...
;         const int klo = kbase0 + 32 * sub;
;         bool full, none;
;         if (MODE == 0) { full = lanesel && (klo + 31 <= t); none = !lanesel || (klo > t); }
;         else { full = (klo + 31 <= t) && (klo >= t - 511); none = (klo > t) || (klo + 31 < t - 511); }
;         if (__all(none)) continue;
;         int dbase = t - klo - 4 * hi;
;         asm volatile("" : "+v"(dbase));
;         const float b0 = none ? -1e30f : -slope2 * (float)dbase;
;         f32x16 s;
; #pragma unroll
;         for (int i = 0; i < 16; ++i) s[i] = fmaf(slope2, (float)((i & 3) + 8 * (i >> 2)), b0);
; #pragma unroll
;         for (int st = 0; st < 4; ++st) {
;             const bf16x8 a = *(LAS const bf16x8*)(buf + (32 * sub + c) * 144 + st * 32 + hi * 16);
;             s = MFMA32(a, qf[st], s);
;         }
;         if (__any(!full && !none)) {
; #pragma unroll
;             for (int i = 0; i < 16; ++i) {
;                 const int dist = dbase - ((i & 3) + 8 * (i >> 2));
;                 const bool valid = (MODE == 0) ? (lanesel && dist >= 0) : ((unsigned)dist < 512u);
;                 if (!valid) s[i] = -1e30f;
;             }
;         }
;     ...
;         float ps = 0.f;
; #pragma unroll
;         for (int i = 0; i < 16; ++i) { const float pv = fexp2(s[i] - m); s[i] = pv; ps += pv; }
;         l += ps;
;         const bf16x8 pb0 = packp(s, 0), pb1 = packp(s, 1);
; #pragma unroll
;         for (int db = 0; db < 2; ++db)
; #pragma unroll
;             for (int tt = 0; tt < 2; ++tt) {
;                 LAS const unsigned char* ap = buf + 9216 + (32 * db + c) * 136 + (32 * sub + 16 * tt + 4 * hi) * 2;
;                 const bf16x8 a = cat4(*(LAS const bf16x4*)ap, *(LAS const bf16x4*)(ap + 16));
;                 o[db] = MFMA32(a, tt == 0 ? pb0 : pb1, o[db]);
;             }
.LBB0_852:
	v_exp_f32_e32 v182, v112
	v_exp_f32_e32 v183, v113
	v_exp_f32_e32 v184, v114
	v_exp_f32_e32 v185, v115
	v_add_f32_e32 v112, 0, v182
	v_add_f32_e32 v112, v183, v112
	v_add_f32_e32 v112, v184, v112
	v_add_f32_e32 v186, v185, v112
	v_exp_f32_e32 v187, v116
	v_exp_f32_e32 v188, v117
	v_exp_f32_e32 v189, v118
	v_exp_f32_e32 v190, v119
	v_exp_f32_e32 v191, v120
	v_exp_f32_e32 v192, v121
	v_exp_f32_e32 v193, v122
	v_exp_f32_e32 v194, v123
	v_mov_b32_e32 v112, v124
	v_add3_u32 v124, s10, v15, v174
	v_exp_f32_e32 v195, v112
	v_add_u32_e32 v120, 0x2000, v124
	v_exp_f32_e32 v196, v125
	ds_read2_b64 v[112:115], v120 offset0:128 offset1:130
	v_exp_f32_e32 v197, v126
	v_cvt_pk_bf16_f32 v116, v182, v183
	v_cvt_pk_bf16_f32 v117, v184, v185
	v_cvt_pk_bf16_f32 v118, v187, v188
	v_cvt_pk_bf16_f32 v119, v189, v190
	ds_read2_b64 v[120:123], v120 offset0:132 offset1:134
	s_waitcnt lgkmcnt(1)
	v_mfma_f32_32x32x16_bf16 v[96:111], v[112:115], v[116:119], v[96:111]
	v_exp_f32_e32 v182, v127
	v_add_u32_e32 v183, 0x3000, v124
	ds_read2_b64 v[124:127], v183 offset0:160 offset1:162
	v_cvt_pk_bf16_f32 v112, v191, v192
	v_cvt_pk_bf16_f32 v113, v193, v194
	v_cvt_pk_bf16_f32 v114, v195, v196
	v_cvt_pk_bf16_f32 v115, v197, v182
	s_waitcnt lgkmcnt(0)
	v_mfma_f32_32x32x16_bf16 v[80:95], v[124:127], v[116:119], v[80:95]
	v_mfma_f32_32x32x16_bf16 v[96:111], v[120:123], v[112:115], v[96:111]
	v_add_f32_e32 v120, v187, v186
	v_add_f32_e32 v120, v188, v120
	v_add_f32_e32 v120, v189, v120
	v_add_f32_e32 v120, v190, v120
	v_add_f32_e32 v120, v191, v120
	v_add_f32_e32 v184, v192, v120
	ds_read2_b64 v[120:123], v183 offset0:164 offset1:166
	s_waitcnt lgkmcnt(0)
	v_mfma_f32_32x32x16_bf16 v[80:95], v[120:123], v[112:115], v[80:95]
	v_add_f32_e32 v116, v193, v184
	v_add_f32_e32 v116, v194, v116
	v_add_f32_e32 v116, v195, v116
	v_add_f32_e32 v116, v196, v116
	v_add_f32_e32 v116, v197, v116
	v_add_f32_e32 v116, v182, v116
	v_add_f32_e32 v161, v161, v116
.LBB0_853:
	s_add_i32 s4, s8, 32
	v_cmp_gt_i32_e32 vcc, s4, v150
	v_cmp_lt_i32_e64 s[2:3], s11, v178
	s_or_b64 vcc, vcc, s[2:3]
	v_cndmask_b32_e64 v112, 0, 1, vcc
	v_cmp_ne_u32_e64 s[2:3], 0, v112
	s_cmp_eq_u64 s[2:3], exec
	s_cbranch_scc1 .LBB0_859
	v_mov_b32_e32 v182, v179
	ds_read_b128 v[184:187], v181 offset:4608
	ds_read_b128 v[188:191], v181 offset:4640
	v_cvt_f32_i32_e32 v112, v182
	v_cmp_gt_i32_e64 s[2:3], s11, v150
	v_cmp_lt_i32_e64 s[4:5], s4, v178
	s_or_b64 s[2:3], s[2:3], s[4:5]
	v_mul_f32_e64 v112, -v152, v112
	v_cndmask_b32_e32 v126, v112, v164, vcc
	v_sub_f32_e32 v126, v126, v249
	v_fma_f32 v112, 0, v152, v126
	v_add_f32_e32 v113, v152, v126
	v_pk_fma_f32 v[114:115], v[152:153], s[72:73], v[126:127] op_sel_hi:[1,1,0]
	v_pk_fma_f32 v[116:117], v[152:153], s[74:75], v[126:127] op_sel_hi:[1,1,0]
	v_pk_fma_f32 v[118:119], v[152:153], s[76:77], v[126:127] op_sel_hi:[1,1,0]
	v_pk_fma_f32 v[120:121], v[152:153], s[70:71], v[126:127] op_sel_hi:[1,1,0]
	v_pk_fma_f32 v[122:123], v[152:153], s[78:79], v[126:127] op_sel_hi:[1,1,0]
	v_pk_fma_f32 v[124:125], v[152:153], s[80:81], v[126:127] op_sel_hi:[1,1,0]
	v_pk_fma_f32 v[126:127], v[152:153], s[82:83], v[126:127] op_sel_hi:[1,1,0]
	s_xor_b64 s[4:5], vcc, -1
	s_and_b64 s[2:3], s[2:3], s[4:5]
	s_waitcnt lgkmcnt(1)
	v_mfma_f32_32x32x16_bf16 v[112:127], v[184:187], v[128:131], v[112:127]
	s_waitcnt lgkmcnt(0)
	v_mfma_f32_32x32x16_bf16 v[112:127], v[188:191], v[132:135], v[112:127]
	ds_read_b128 v[184:187], v181 offset:4672
	ds_read_b128 v[188:191], v181 offset:4704
	v_cndmask_b32_e64 v181, 0, 1, s[2:3]
	v_cmp_ne_u32_e32 vcc, 0, v181
	s_waitcnt lgkmcnt(1)
	v_mfma_f32_32x32x16_bf16 v[112:127], v[184:187], v[136:139], v[112:127]
	s_waitcnt lgkmcnt(0)
	v_mfma_f32_32x32x16_bf16 v[112:127], v[188:191], v[140:143], v[112:127]
	s_cbranch_vccz .LBB0_856
	v_cmp_gt_u32_e32 vcc, s89, v182
	v_add_u32_e32 v181, -1, v182
	s_nop 8
	v_cndmask_b32_e32 v112, v164, v112, vcc
	v_cmp_gt_u32_e32 vcc, s89, v181
	v_add_u32_e32 v181, -2, v182
	s_nop 0
	v_cndmask_b32_e32 v113, v164, v113, vcc
	v_cmp_gt_u32_e32 vcc, s89, v181
	v_add_u32_e32 v181, -3, v182
	s_nop 0
	v_cndmask_b32_e32 v114, v164, v114, vcc
	v_cmp_gt_u32_e32 vcc, s89, v181
	v_add_u32_e32 v181, -8, v182
	s_nop 0
	v_cndmask_b32_e32 v115, v164, v115, vcc
	v_cmp_gt_u32_e32 vcc, s89, v181
	v_add_u32_e32 v181, -9, v182
	s_nop 0
	v_cndmask_b32_e32 v116, v164, v116, vcc
	v_cmp_gt_u32_e32 vcc, s89, v181
	v_add_u32_e32 v181, -10, v182
	s_nop 0
	v_cndmask_b32_e32 v117, v164, v117, vcc
	v_cmp_gt_u32_e32 vcc, s89, v181
	v_add_u32_e32 v181, -11, v182
	s_nop 0
	v_cndmask_b32_e32 v118, v164, v118, vcc
	v_cmp_gt_u32_e32 vcc, s89, v181
	v_add_u32_e32 v181, -16, v182
	s_nop 0
	v_cndmask_b32_e32 v119, v164, v119, vcc
	v_cmp_gt_u32_e32 vcc, s89, v181
	v_subrev_u32_e32 v181, 17, v182
	s_nop 0
	v_cndmask_b32_e32 v120, v164, v120, vcc
	v_cmp_gt_u32_e32 vcc, s89, v181
	v_subrev_u32_e32 v181, 18, v182
	s_nop 0
	v_cndmask_b32_e32 v121, v164, v121, vcc
	v_cmp_gt_u32_e32 vcc, s89, v181
	v_subrev_u32_e32 v181, 19, v182
	s_nop 0
	v_cndmask_b32_e32 v122, v164, v122, vcc
	v_cmp_gt_u32_e32 vcc, s89, v181
	v_subrev_u32_e32 v181, 24, v182
	s_nop 0
	v_cndmask_b32_e32 v123, v164, v123, vcc
	v_cmp_gt_u32_e32 vcc, s89, v181
	v_subrev_u32_e32 v181, 25, v182
	s_nop 0
	v_cndmask_b32_e32 v124, v164, v124, vcc
	v_cmp_gt_u32_e32 vcc, s89, v181
	v_subrev_u32_e32 v181, 26, v182
	s_nop 0
	v_cndmask_b32_e32 v125, v164, v125, vcc
	v_cmp_gt_u32_e32 vcc, s89, v181
	v_subrev_u32_e32 v181, 27, v182
	s_nop 0
	v_cndmask_b32_e32 v126, v164, v126, vcc
	v_cmp_gt_u32_e32 vcc, s89, v181
	s_nop 1
	v_cndmask_b32_e32 v127, v164, v127, vcc
; #define LAS __attribute__((address_space(3)))
; DI float xhalf_max(float v) { unsigned a = __builtin_bit_cast(unsigned, v), b = a; swap32(a, b); return fmaxf(__builtin_bit_cast(float, a), __builtin_bit_cast(float, b)); }
; DI float fexp2(float x) { return __builtin_amdgcn_exp2f(x); }
; #define MFMA32(a, b, c) __builtin_amdgcn_mfma_f32_32x32x16_bf16((a), (b), (c), 0, 0, 0)
; template <int MODE>
; DI void nsa_tile(LAS const unsigned char* buf, const bf16x8 (&qf)[4], f32x16 (&o)[2], float& m, float& l, int kbase0, int t, bool lanesel, float slope2, int c, int hi) {
;     ...
;         float mx = max16(s);
;         mx = xhalf_max(mx);
;         if (__any(mx > m + 8.f)) {
;             const float mn = fmaxf(m, mx), alpha = fexp2(m - mn); m = mn; l *= alpha;
;             o[0] = o[0] * alpha; o[1] = o[1] * alpha;
;         }
;         float ps = 0.f;
; #pragma unroll
;         for (int i = 0; i < 16; ++i) { const float pv = fexp2(s[i] - m); s[i] = pv; ps += pv; }
;         l += ps;
;         const bf16x8 pb0 = packp(s, 0), pb1 = packp(s, 1);
; #pragma unroll
;         for (int db = 0; db < 2; ++db)
; #pragma unroll
;             for (int tt = 0; tt < 2; ++tt) {
;                 LAS const unsigned char* ap = buf + 9216 + (32 * db + c) * 136 + (32 * sub + 16 * tt + 4 * hi) * 2;
;                 const bf16x8 a = cat4(*(LAS const bf16x4*)ap, *(LAS const bf16x4*)(ap + 16));
;                 o[db] = MFMA32(a, tt == 0 ? pb0 : pb1, o[db]);
;             }
.LBB0_856:
	v_max3_f32 v181, v112, v113, v114
	v_max3_f32 v182, v115, v116, v117
	v_max3_f32 v183, v118, v119, v120
	v_max3_f32 v184, v121, v122, v123
	s_nop 0
	v_max3_f32 v181, v181, v124, v125
	v_max3_f32 v182, v182, v126, v127
	s_nop 0
	v_max3_f32 v181, v181, v182, v183
	s_nop 0
	v_max3_f32 v181, v181, v184, v184
	s_nop 0
	v_mov_b32_e32 v182, v181
	s_nop 1
	v_permlane32_swap_b32 v181, v182
	s_nop 0
	v_max_f32_e32 v182, v182, v182
	v_max_f32_e32 v181, v181, v181
	v_max_f32_e32 v181, v181, v182
	v_add_f32_e32 v181, v181, v249
	v_add_f32_e32 v182, 0x41000000, v180
	v_cmp_gt_f32_e32 vcc, v181, v182
	s_cbranch_vccz .LBB0_858
	v_max_f32_e32 v181, v181, v181
	v_max_f32_e32 v182, v180, v180
	v_max_f32_e32 v181, v182, v181
	v_sub_f32_e32 v180, v180, v181
	v_exp_f32_e32 v180, v180
	s_nop 0
	v_mul_f32_e32 v161, v161, v180
	v_pk_mul_f32 v[110:111], v[110:111], v[180:181] op_sel_hi:[1,0]
	v_pk_mul_f32 v[108:109], v[108:109], v[180:181] op_sel_hi:[1,0]
	v_pk_mul_f32 v[106:107], v[106:107], v[180:181] op_sel_hi:[1,0]
	v_pk_mul_f32 v[104:105], v[104:105], v[180:181] op_sel_hi:[1,0]
	v_pk_mul_f32 v[102:103], v[102:103], v[180:181] op_sel_hi:[1,0]
	v_pk_mul_f32 v[100:101], v[100:101], v[180:181] op_sel_hi:[1,0]
	v_pk_mul_f32 v[98:99], v[98:99], v[180:181] op_sel_hi:[1,0]
	v_pk_mul_f32 v[96:97], v[96:97], v[180:181] op_sel_hi:[1,0]
	v_pk_mul_f32 v[94:95], v[94:95], v[180:181] op_sel_hi:[1,0]
	v_pk_mul_f32 v[92:93], v[92:93], v[180:181] op_sel_hi:[1,0]
	v_pk_mul_f32 v[90:91], v[90:91], v[180:181] op_sel_hi:[1,0]
	v_pk_mul_f32 v[88:89], v[88:89], v[180:181] op_sel_hi:[1,0]
	v_pk_mul_f32 v[86:87], v[86:87], v[180:181] op_sel_hi:[1,0]
	v_pk_mul_f32 v[84:85], v[84:85], v[180:181] op_sel_hi:[1,0]
	v_pk_mul_f32 v[82:83], v[82:83], v[180:181] op_sel_hi:[1,0]
	v_pk_mul_f32 v[80:81], v[80:81], v[180:181] op_sel_hi:[1,0]
	v_mov_b32_e32 v180, v181
	v_cmp_lt_f32_e32 vcc, 0xdf0ac723, v180
	s_nop 1
	v_cndmask_b32_e32 v250, 0, v180, vcc
	v_sub_f32_e32 v251, v250, v249
	v_mov_b32_e32 v249, v250
	v_sub_f32_e32 v112, v112, v251
	v_sub_f32_e32 v113, v113, v251
	v_sub_f32_e32 v114, v114, v251
	v_sub_f32_e32 v115, v115, v251
	v_sub_f32_e32 v116, v116, v251
	v_sub_f32_e32 v117, v117, v251
	v_sub_f32_e32 v118, v118, v251
	v_sub_f32_e32 v119, v119, v251
	v_sub_f32_e32 v120, v120, v251
	v_sub_f32_e32 v121, v121, v251
	v_sub_f32_e32 v122, v122, v251
	v_sub_f32_e32 v123, v123, v251
	v_sub_f32_e32 v124, v124, v251
	v_sub_f32_e32 v125, v125, v251
	v_sub_f32_e32 v126, v126, v251
	v_sub_f32_e32 v127, v127, v251
.LBB0_858:
	v_exp_f32_e32 v181, v112
	v_exp_f32_e32 v182, v113
	v_exp_f32_e32 v183, v114
	v_exp_f32_e32 v184, v115
	v_add_f32_e32 v112, 0, v181
	v_add_f32_e32 v112, v182, v112
	v_add_f32_e32 v112, v183, v112
	v_add_f32_e32 v185, v184, v112
	v_exp_f32_e32 v186, v116
	v_exp_f32_e32 v187, v117
	v_exp_f32_e32 v188, v118
	v_exp_f32_e32 v189, v119
	v_exp_f32_e32 v190, v120
	v_exp_f32_e32 v191, v121
	v_exp_f32_e32 v192, v122
	v_exp_f32_e32 v193, v123
	v_exp_f32_e32 v194, v124
	v_exp_f32_e32 v195, v125
	v_add3_u32 v112, s10, v15, v174
	v_add_u32_e32 v120, 0x2000, v112
	ds_read2_b64 v[112:115], v120 offset0:136 offset1:138
	v_exp_f32_e32 v196, v126
	v_exp_f32_e32 v197, v127
	v_cvt_pk_bf16_f32 v116, v181, v182
	v_cvt_pk_bf16_f32 v117, v183, v184
	v_cvt_pk_bf16_f32 v118, v186, v187
	v_cvt_pk_bf16_f32 v119, v188, v189
	ds_read2_b64 v[120:123], v120 offset0:140 offset1:142
	v_add3_u32 v124, s10, v176, v174
	s_waitcnt lgkmcnt(1)
	v_mfma_f32_32x32x16_bf16 v[96:111], v[112:115], v[116:119], v[96:111]
	v_add_u32_e32 v181, 0x2000, v124
	ds_read2_b64 v[124:127], v181 offset0:136 offset1:138
	v_cvt_pk_bf16_f32 v112, v190, v191
	v_cvt_pk_bf16_f32 v113, v192, v193
	v_cvt_pk_bf16_f32 v114, v194, v195
	v_cvt_pk_bf16_f32 v115, v196, v197
	s_waitcnt lgkmcnt(0)
	v_mfma_f32_32x32x16_bf16 v[80:95], v[124:127], v[116:119], v[80:95]
	v_mfma_f32_32x32x16_bf16 v[96:111], v[120:123], v[112:115], v[96:111]
	v_add_f32_e32 v120, v186, v185
	v_add_f32_e32 v120, v187, v120
	v_add_f32_e32 v120, v188, v120
	v_add_f32_e32 v120, v189, v120
	v_add_f32_e32 v120, v190, v120
	v_add_f32_e32 v182, v191, v120
	ds_read2_b64 v[120:123], v181 offset0:140 offset1:142
	s_waitcnt lgkmcnt(0)
	v_mfma_f32_32x32x16_bf16 v[80:95], v[120:123], v[112:115], v[80:95]
	v_add_f32_e32 v116, v192, v182
	v_add_f32_e32 v116, v193, v116
	v_add_f32_e32 v116, v194, v116
	v_add_f32_e32 v116, v195, v116
	v_add_f32_e32 v116, v196, v116
	v_add_f32_e32 v116, v197, v116
	v_add_f32_e32 v161, v161, v116

; __global__ void __launch_bounds__(NTHREADS, 2) fwd_megakernel(Params p) {
;     extern __shared__ __attribute__((aligned(16))) unsigned char dyn_lds[];
	.amdhsa_kernel _Z14fwd_megakernel6Params
		.amdhsa_group_segment_fixed_size 0
		.amdhsa_private_segment_fixed_size 0
		.amdhsa_kernarg_size 432
		.amdhsa_user_sgpr_count 2
		.amdhsa_user_sgpr_dispatch_ptr 0
		.amdhsa_user_sgpr_queue_ptr 0
		.amdhsa_user_sgpr_kernarg_segment_ptr 1
		.amdhsa_user_sgpr_dispatch_id 0
		.amdhsa_user_sgpr_kernarg_preload_length 0
		.amdhsa_user_sgpr_kernarg_preload_offset 0
		.amdhsa_user_sgpr_private_segment_size 0
		.amdhsa_uses_dynamic_stack 0
		.amdhsa_enable_private_segment 0
		.amdhsa_system_sgpr_workgroup_id_x 1
		.amdhsa_system_sgpr_workgroup_id_y 0
		.amdhsa_system_sgpr_workgroup_id_z 0
		.amdhsa_system_sgpr_workgroup_info 0
		.amdhsa_system_vgpr_workitem_id 2
		.amdhsa_next_free_vgpr 252
		.amdhsa_next_free_sgpr 102
		.amdhsa_accum_offset 252
		.amdhsa_reserve_vcc 1
		.amdhsa_float_round_mode_32 0
		.amdhsa_float_round_mode_16_64 0
		.amdhsa_float_denorm_mode_32 3
		.amdhsa_float_denorm_mode_16_64 3
		.amdhsa_dx10_clamp 1
		.amdhsa_ieee_mode 1
		.amdhsa_fp16_overflow 0
		.amdhsa_tg_split 0
		.amdhsa_exception_fp_ieee_invalid_op 0
		.amdhsa_exception_fp_denorm_src 0
		.amdhsa_exception_fp_ieee_div_zero 0
		.amdhsa_exception_fp_ieee_overflow 0
		.amdhsa_exception_fp_ieee_underflow 0
		.amdhsa_exception_fp_ieee_inexact 0
		.amdhsa_exception_int_div_zero 0
	.end_amdhsa_kernel

; __global__ void __launch_bounds__(NTHREADS, 2) fwd_megakernel(Params p) {
;     extern __shared__ __attribute__((aligned(16))) unsigned char dyn_lds[];
amdhsa.kernels:
  - .agpr_count:     0
    .args:
      - .offset:         0
        .size:           176
        .value_kind:     by_value
      - .offset:         176
        .size:           4
        .value_kind:     hidden_block_count_x
      - .offset:         180
        .size:           4
        .value_kind:     hidden_block_count_y
      - .offset:         184
        .size:           4
        .value_kind:     hidden_block_count_z
      - .offset:         188
        .size:           2
        .value_kind:     hidden_group_size_x
      - .offset:         190
        .size:           2
        .value_kind:     hidden_group_size_y
      - .offset:         192
        .size:           2
        .value_kind:     hidden_group_size_z
      - .offset:         194
        .size:           2
        .value_kind:     hidden_remainder_x
      - .offset:         196
        .size:           2
        .value_kind:     hidden_remainder_y
      - .offset:         198
        .size:           2
        .value_kind:     hidden_remainder_z
      - .offset:         216
        .size:           8
        .value_kind:     hidden_global_offset_x
      - .offset:         224
        .size:           8
        .value_kind:     hidden_global_offset_y
      - .offset:         232
        .size:           8
        .value_kind:     hidden_global_offset_z
      - .offset:         240
        .size:           2
        .value_kind:     hidden_grid_dims
      - .offset:         264
        .size:           8
        .value_kind:     hidden_multigrid_sync_arg
      - .offset:         296
        .size:           4
        .value_kind:     hidden_dynamic_lds_size
    .group_segment_fixed_size: 0
    .kernarg_segment_align: 8
    .kernarg_segment_size: 432
    .language:       OpenCL C
    .language_version:
      - 2
      - 0
    .max_flat_workgroup_size: 512
    .name:           _Z14fwd_megakernel6Params
    .private_segment_fixed_size: 0
    .sgpr_count:     108
    .sgpr_spill_count: 36
    .symbol:         _Z14fwd_megakernel6Params.kd
    .uniform_work_group_size: 1
    .uses_dynamic_stack: false
    .vgpr_count:     252
    .vgpr_spill_count: 0
    .wavefront_size: 64
